# P6 epilogue: non-temporal hint on the read-once f32 residual loads
# baseline (speedup 1.0000x reference)
.LBB0_774:
	s_lshl_b32 s29, s6, 8
	s_sub_i32 s6, s20, 32
	s_lshr_b32 s6, s6, 4
	s_cmp_lt_i32 s20, 32
	s_mulk_i32 s6, 0x1800
	s_cselect_b32 s6, 0xc000, s6
	s_cselect_b32 s42, s16, s56
	s_cselect_b32 s43, s17, s57
	s_add_i32 s6, s6, s29
	s_addk_i32 s6, 0x800
	s_lshl_b32 s6, s6, 2
	s_add_u32 s40, s78, s6
	s_addc_u32 s41, s79, 0
	v_lshlrev_b32_e32 v158, 2, v160
	s_lshl_b32 s31, s20, 20
	s_lshl_b32 s29, s29, 2
	s_add_u32 s31, s31, s29
	global_load_dwordx4 v[32:35], v158, s[40:41]
	global_load_dwordx4 v[36:39], v158, s[40:41] offset:16
	global_load_dwordx4 v[44:47], v158, s[40:41] offset:128
	global_load_dwordx4 v[40:43], v158, s[40:41] offset:144
	s_add_u32 s44, s42, s31
	s_addc_u32 s45, s43, 0
	s_lshr_b32 s31, s31, 1
	s_add_u32 s42, s76, s31
	s_addc_u32 s43, s77, 0
	v_lshlrev_b32_e32 v159, 12, v161
	v_lshl_add_u32 v159, v148, 2, v159
	v_add_u32_e32 v226, 0x8000, v159
	v_lshrrev_b32_e32 v227, 1, v159
	v_add_u32_e32 v228, 0x4000, v227
	global_load_dwordx4 v[168:171], v159, s[44:45] nt
	global_load_dwordx4 v[172:175], v159, s[44:45] offset:16 nt
	global_load_dwordx4 v[176:179], v226, s[44:45] nt
	global_load_dwordx4 v[180:183], v226, s[44:45] offset:16 nt
	s_add_u32 s44, s44, 0x10000
	s_addc_u32 s45, s45, 0
	global_load_dwordx4 v[184:187], v159, s[44:45] nt
	global_load_dwordx4 v[188:191], v159, s[44:45] offset:16 nt
	global_load_dwordx4 v[192:195], v226, s[44:45] nt
	global_load_dwordx4 v[196:199], v226, s[44:45] offset:16 nt
	s_add_u32 s44, s44, 0x10000
	s_addc_u32 s45, s45, 0
	global_load_dwordx4 v[200:203], v159, s[44:45] nt
	global_load_dwordx4 v[204:207], v159, s[44:45] offset:16 nt
	global_load_dwordx4 v[218:221], v226, s[44:45] nt
	global_load_dwordx4 v[222:225], v226, s[44:45] offset:16 nt
	s_waitcnt vmcnt(12)
	v_pk_mul_f32 v[140:141], v[140:141], v[32:33]
	v_pk_mul_f32 v[142:143], v[142:143], v[34:35]
	v_pk_mul_f32 v[136:137], v[136:137], v[36:37]
	v_pk_mul_f32 v[138:139], v[138:139], v[38:39]
	v_pk_mul_f32 v[132:133], v[132:133], v[44:45]
	v_pk_mul_f32 v[134:135], v[134:135], v[46:47]
	v_pk_mul_f32 v[128:129], v[128:129], v[40:41]
	v_pk_mul_f32 v[130:131], v[130:131], v[42:43]
	v_pk_mul_f32 v[124:125], v[124:125], v[32:33]
	v_pk_mul_f32 v[126:127], v[126:127], v[34:35]
	v_pk_mul_f32 v[120:121], v[120:121], v[36:37]
	v_pk_mul_f32 v[122:123], v[122:123], v[38:39]
	v_pk_mul_f32 v[116:117], v[116:117], v[44:45]
	v_pk_mul_f32 v[118:119], v[118:119], v[46:47]
	v_pk_mul_f32 v[112:113], v[112:113], v[40:41]
	v_pk_mul_f32 v[114:115], v[114:115], v[42:43]
	v_pk_mul_f32 v[108:109], v[108:109], v[32:33]
	v_pk_mul_f32 v[110:111], v[110:111], v[34:35]
	v_pk_mul_f32 v[104:105], v[104:105], v[36:37]
	v_pk_mul_f32 v[106:107], v[106:107], v[38:39]
	v_pk_mul_f32 v[100:101], v[100:101], v[44:45]
	v_pk_mul_f32 v[102:103], v[102:103], v[46:47]
	v_pk_mul_f32 v[96:97], v[96:97], v[40:41]
	v_pk_mul_f32 v[98:99], v[98:99], v[42:43]
	v_pk_mul_f32 v[92:93], v[92:93], v[32:33]
	v_pk_mul_f32 v[94:95], v[94:95], v[34:35]
	v_pk_mul_f32 v[88:89], v[88:89], v[36:37]
	v_pk_mul_f32 v[90:91], v[90:91], v[38:39]
	v_pk_mul_f32 v[84:85], v[84:85], v[44:45]
	v_pk_mul_f32 v[86:87], v[86:87], v[46:47]
	v_pk_mul_f32 v[80:81], v[80:81], v[40:41]
	v_pk_mul_f32 v[82:83], v[82:83], v[42:43]
	v_pk_mul_f32 v[76:77], v[76:77], v[32:33]
	v_pk_mul_f32 v[78:79], v[78:79], v[34:35]
	v_pk_mul_f32 v[72:73], v[72:73], v[36:37]
	v_pk_mul_f32 v[74:75], v[74:75], v[38:39]
	v_pk_mul_f32 v[68:69], v[68:69], v[44:45]
	v_pk_mul_f32 v[70:71], v[70:71], v[46:47]
	v_pk_mul_f32 v[64:65], v[64:65], v[40:41]
	v_pk_mul_f32 v[66:67], v[66:67], v[42:43]
	v_pk_mul_f32 v[60:61], v[60:61], v[32:33]
	v_pk_mul_f32 v[62:63], v[62:63], v[34:35]
	v_pk_mul_f32 v[56:57], v[56:57], v[36:37]
	v_pk_mul_f32 v[58:59], v[58:59], v[38:39]
	v_pk_mul_f32 v[52:53], v[52:53], v[44:45]
	v_pk_mul_f32 v[54:55], v[54:55], v[46:47]
	v_pk_mul_f32 v[48:49], v[48:49], v[40:41]
	v_pk_mul_f32 v[50:51], v[50:51], v[42:43]
	v_pk_mul_f32 v[28:29], v[28:29], v[32:33]
	v_pk_mul_f32 v[30:31], v[30:31], v[34:35]
	v_pk_mul_f32 v[24:25], v[24:25], v[36:37]
	v_pk_mul_f32 v[26:27], v[26:27], v[38:39]
	v_pk_mul_f32 v[20:21], v[20:21], v[44:45]
	v_pk_mul_f32 v[22:23], v[22:23], v[46:47]
	v_pk_mul_f32 v[16:17], v[16:17], v[40:41]
	v_pk_mul_f32 v[18:19], v[18:19], v[42:43]
	v_pk_mul_f32 v[12:13], v[12:13], v[32:33]
	v_pk_mul_f32 v[14:15], v[14:15], v[34:35]
	v_pk_mul_f32 v[8:9], v[8:9], v[36:37]
	v_pk_mul_f32 v[10:11], v[10:11], v[38:39]
	v_pk_mul_f32 v[4:5], v[4:5], v[44:45]
	v_pk_mul_f32 v[6:7], v[6:7], v[46:47]
	v_pk_mul_f32 v[0:1], v[0:1], v[40:41]
	v_pk_mul_f32 v[2:3], v[2:3], v[42:43]
	v_cvt_pk_bf16_f32 v140, v140, v141
	v_cvt_pk_bf16_f32 v141, v142, v143
	v_cvt_pk_bf16_f32 v142, v136, v137
	v_cvt_pk_bf16_f32 v143, v138, v139
	v_cvt_pk_bf16_f32 v132, v132, v133
	v_cvt_pk_bf16_f32 v133, v134, v135
	v_cvt_pk_bf16_f32 v134, v128, v129
	v_cvt_pk_bf16_f32 v135, v130, v131
	v_cvt_pk_bf16_f32 v124, v124, v125
	v_cvt_pk_bf16_f32 v125, v126, v127
	v_cvt_pk_bf16_f32 v126, v120, v121
	v_cvt_pk_bf16_f32 v127, v122, v123
	v_cvt_pk_bf16_f32 v116, v116, v117
	v_cvt_pk_bf16_f32 v117, v118, v119
	v_cvt_pk_bf16_f32 v118, v112, v113
	v_cvt_pk_bf16_f32 v119, v114, v115
	v_cvt_pk_bf16_f32 v108, v108, v109
	v_cvt_pk_bf16_f32 v109, v110, v111
	v_cvt_pk_bf16_f32 v110, v104, v105
	v_cvt_pk_bf16_f32 v111, v106, v107
	v_cvt_pk_bf16_f32 v100, v100, v101
	v_cvt_pk_bf16_f32 v101, v102, v103
	v_cvt_pk_bf16_f32 v102, v96, v97
	v_cvt_pk_bf16_f32 v103, v98, v99
	v_cvt_pk_bf16_f32 v92, v92, v93
	v_cvt_pk_bf16_f32 v93, v94, v95
	v_cvt_pk_bf16_f32 v94, v88, v89
	v_cvt_pk_bf16_f32 v95, v90, v91
	v_cvt_pk_bf16_f32 v84, v84, v85
	v_cvt_pk_bf16_f32 v85, v86, v87
	v_cvt_pk_bf16_f32 v86, v80, v81
	v_cvt_pk_bf16_f32 v87, v82, v83
	v_cvt_pk_bf16_f32 v76, v76, v77
	v_cvt_pk_bf16_f32 v77, v78, v79
	v_cvt_pk_bf16_f32 v78, v72, v73
	v_cvt_pk_bf16_f32 v79, v74, v75
	v_cvt_pk_bf16_f32 v68, v68, v69
	v_cvt_pk_bf16_f32 v69, v70, v71
	v_cvt_pk_bf16_f32 v70, v64, v65
	v_cvt_pk_bf16_f32 v71, v66, v67
	v_cvt_pk_bf16_f32 v60, v60, v61
	v_cvt_pk_bf16_f32 v61, v62, v63
	v_cvt_pk_bf16_f32 v62, v56, v57
	v_cvt_pk_bf16_f32 v63, v58, v59
	v_cvt_pk_bf16_f32 v52, v52, v53
	v_cvt_pk_bf16_f32 v53, v54, v55
	v_cvt_pk_bf16_f32 v54, v48, v49
	v_cvt_pk_bf16_f32 v55, v50, v51
	v_cvt_pk_bf16_f32 v28, v28, v29
	v_cvt_pk_bf16_f32 v29, v30, v31
	v_cvt_pk_bf16_f32 v30, v24, v25
	v_cvt_pk_bf16_f32 v31, v26, v27
	v_cvt_pk_bf16_f32 v20, v20, v21
	v_cvt_pk_bf16_f32 v21, v22, v23
	v_cvt_pk_bf16_f32 v22, v16, v17
	v_cvt_pk_bf16_f32 v23, v18, v19
	v_cvt_pk_bf16_f32 v12, v12, v13
	v_cvt_pk_bf16_f32 v13, v14, v15
	v_cvt_pk_bf16_f32 v14, v8, v9
	v_cvt_pk_bf16_f32 v15, v10, v11
	v_cvt_pk_bf16_f32 v4, v4, v5
	v_cvt_pk_bf16_f32 v5, v6, v7
	v_cvt_pk_bf16_f32 v6, v0, v1
	v_cvt_pk_bf16_f32 v7, v2, v3
	s_add_u32 s44, s44, 0x10000
	s_addc_u32 s45, s45, 0
	global_load_dwordx4 v[32:35], v159, s[44:45] nt
	global_load_dwordx4 v[36:39], v159, s[44:45] offset:16 nt
	global_load_dwordx4 v[40:43], v226, s[44:45] nt
	global_load_dwordx4 v[44:47], v226, s[44:45] offset:16 nt
	s_add_u32 s44, s44, 0x50000
	s_addc_u32 s45, s45, 0
	global_load_dwordx4 v[128:131], v159, s[44:45] nt
	global_load_dwordx4 v[136:139], v159, s[44:45] offset:16 nt
	global_load_dwordx4 v[112:115], v226, s[44:45] nt
	global_load_dwordx4 v[120:123], v226, s[44:45] offset:16 nt
	s_add_u32 s44, s44, 0x10000
	s_addc_u32 s45, s45, 0
	global_load_dwordx4 v[96:99], v159, s[44:45] nt
	global_load_dwordx4 v[104:107], v159, s[44:45] offset:16 nt
	global_load_dwordx4 v[80:83], v226, s[44:45] nt
	global_load_dwordx4 v[88:91], v226, s[44:45] offset:16 nt
	s_add_u32 s44, s44, 0x10000
	s_addc_u32 s45, s45, 0
	global_load_dwordx4 v[64:67], v159, s[44:45] nt
	global_load_dwordx4 v[72:75], v159, s[44:45] offset:16 nt
	global_load_dwordx4 v[48:51], v226, s[44:45] nt
	global_load_dwordx4 v[56:59], v226, s[44:45] offset:16 nt
	s_add_u32 s44, s44, 0x10000
	s_addc_u32 s45, s45, 0
	global_load_dwordx4 v[16:19], v159, s[44:45] nt
	global_load_dwordx4 v[24:27], v159, s[44:45] offset:16 nt
	global_load_dwordx4 v[0:3], v226, s[44:45] nt
	global_load_dwordx4 v[8:11], v226, s[44:45] offset:16 nt
	ds_write_b128 v165, v[140:143]
	ds_write_b128 v165, v[132:135] offset:64
	ds_read_b128 v[140:143], v166
	ds_read_b128 v[132:135], v166 offset:1152
	s_waitcnt vmcnt(28)
	s_waitcnt lgkmcnt(1)
	v_lshlrev_b32_e32 v230, 16, v140
	v_and_b32_e32 v231, 0xffff0000, v140
	v_pk_add_f32 v[168:169], v[168:169], v[230:231]
	v_lshlrev_b32_e32 v230, 16, v141
	v_and_b32_e32 v231, 0xffff0000, v141
	v_pk_add_f32 v[170:171], v[170:171], v[230:231]
	v_lshlrev_b32_e32 v230, 16, v142
	v_and_b32_e32 v231, 0xffff0000, v142
	v_pk_add_f32 v[172:173], v[172:173], v[230:231]
	v_lshlrev_b32_e32 v230, 16, v143
	v_and_b32_e32 v231, 0xffff0000, v143
	v_pk_add_f32 v[174:175], v[174:175], v[230:231]
	v_cvt_pk_bf16_f32 v140, v168, v169
	v_cvt_pk_bf16_f32 v141, v170, v171
	v_cvt_pk_bf16_f32 v142, v172, v173
	v_cvt_pk_bf16_f32 v143, v174, v175
	global_store_dwordx4 v227, v[140:143], s[42:43]
	s_waitcnt lgkmcnt(0)
	v_lshlrev_b32_e32 v230, 16, v132
	v_and_b32_e32 v231, 0xffff0000, v132
	v_pk_add_f32 v[176:177], v[176:177], v[230:231]
	v_lshlrev_b32_e32 v230, 16, v133
	v_and_b32_e32 v231, 0xffff0000, v133
	v_pk_add_f32 v[178:179], v[178:179], v[230:231]
	v_lshlrev_b32_e32 v230, 16, v134
	v_and_b32_e32 v231, 0xffff0000, v134
	v_pk_add_f32 v[180:181], v[180:181], v[230:231]
	v_lshlrev_b32_e32 v230, 16, v135
	v_and_b32_e32 v231, 0xffff0000, v135
	v_pk_add_f32 v[182:183], v[182:183], v[230:231]
	v_cvt_pk_bf16_f32 v132, v176, v177
	v_cvt_pk_bf16_f32 v133, v178, v179
	v_cvt_pk_bf16_f32 v134, v180, v181
	v_cvt_pk_bf16_f32 v135, v182, v183
	global_store_dwordx4 v228, v[132:135], s[42:43]
	s_add_u32 s42, s42, 0x8000
	s_addc_u32 s43, s43, 0
	ds_write_b128 v165, v[124:127]
	ds_write_b128 v165, v[116:119] offset:64
	ds_read_b128 v[124:127], v166
	ds_read_b128 v[116:119], v166 offset:1152
	s_waitcnt vmcnt(26)
	s_waitcnt lgkmcnt(1)
	v_lshlrev_b32_e32 v230, 16, v124
	v_and_b32_e32 v231, 0xffff0000, v124
	v_pk_add_f32 v[184:185], v[184:185], v[230:231]
	v_lshlrev_b32_e32 v230, 16, v125
	v_and_b32_e32 v231, 0xffff0000, v125
	v_pk_add_f32 v[186:187], v[186:187], v[230:231]
	v_lshlrev_b32_e32 v230, 16, v126
	v_and_b32_e32 v231, 0xffff0000, v126
	v_pk_add_f32 v[188:189], v[188:189], v[230:231]
	v_lshlrev_b32_e32 v230, 16, v127
	v_and_b32_e32 v231, 0xffff0000, v127
	v_pk_add_f32 v[190:191], v[190:191], v[230:231]
	v_cvt_pk_bf16_f32 v124, v184, v185
	v_cvt_pk_bf16_f32 v125, v186, v187
	v_cvt_pk_bf16_f32 v126, v188, v189
	v_cvt_pk_bf16_f32 v127, v190, v191
	global_store_dwordx4 v227, v[124:127], s[42:43]
	s_waitcnt lgkmcnt(0)
	v_lshlrev_b32_e32 v230, 16, v116
	v_and_b32_e32 v231, 0xffff0000, v116
	v_pk_add_f32 v[192:193], v[192:193], v[230:231]
	v_lshlrev_b32_e32 v230, 16, v117
	v_and_b32_e32 v231, 0xffff0000, v117
	v_pk_add_f32 v[194:195], v[194:195], v[230:231]
	v_lshlrev_b32_e32 v230, 16, v118
	v_and_b32_e32 v231, 0xffff0000, v118
	v_pk_add_f32 v[196:197], v[196:197], v[230:231]
	v_lshlrev_b32_e32 v230, 16, v119
	v_and_b32_e32 v231, 0xffff0000, v119
	v_pk_add_f32 v[198:199], v[198:199], v[230:231]
	v_cvt_pk_bf16_f32 v116, v192, v193
	v_cvt_pk_bf16_f32 v117, v194, v195
	v_cvt_pk_bf16_f32 v118, v196, v197
	v_cvt_pk_bf16_f32 v119, v198, v199
	global_store_dwordx4 v228, v[116:119], s[42:43]
	s_add_u32 s42, s42, 0x8000
	s_addc_u32 s43, s43, 0
	ds_write_b128 v165, v[108:111]
	ds_write_b128 v165, v[100:103] offset:64
	ds_read_b128 v[108:111], v166
	ds_read_b128 v[100:103], v166 offset:1152
	s_waitcnt vmcnt(24)
	s_waitcnt lgkmcnt(1)
	v_lshlrev_b32_e32 v230, 16, v108
	v_and_b32_e32 v231, 0xffff0000, v108
	v_pk_add_f32 v[200:201], v[200:201], v[230:231]
	v_lshlrev_b32_e32 v230, 16, v109
	v_and_b32_e32 v231, 0xffff0000, v109
	v_pk_add_f32 v[202:203], v[202:203], v[230:231]
	v_lshlrev_b32_e32 v230, 16, v110
	v_and_b32_e32 v231, 0xffff0000, v110
	v_pk_add_f32 v[204:205], v[204:205], v[230:231]
	v_lshlrev_b32_e32 v230, 16, v111
	v_and_b32_e32 v231, 0xffff0000, v111
	v_pk_add_f32 v[206:207], v[206:207], v[230:231]
	v_cvt_pk_bf16_f32 v108, v200, v201
	v_cvt_pk_bf16_f32 v109, v202, v203
	v_cvt_pk_bf16_f32 v110, v204, v205
	v_cvt_pk_bf16_f32 v111, v206, v207
	global_store_dwordx4 v227, v[108:111], s[42:43]
	s_waitcnt lgkmcnt(0)
	v_lshlrev_b32_e32 v230, 16, v100
	v_and_b32_e32 v231, 0xffff0000, v100
	v_pk_add_f32 v[218:219], v[218:219], v[230:231]
	v_lshlrev_b32_e32 v230, 16, v101
	v_and_b32_e32 v231, 0xffff0000, v101
	v_pk_add_f32 v[220:221], v[220:221], v[230:231]
	v_lshlrev_b32_e32 v230, 16, v102
	v_and_b32_e32 v231, 0xffff0000, v102
	v_pk_add_f32 v[222:223], v[222:223], v[230:231]
	v_lshlrev_b32_e32 v230, 16, v103
	v_and_b32_e32 v231, 0xffff0000, v103
	v_pk_add_f32 v[224:225], v[224:225], v[230:231]
	v_cvt_pk_bf16_f32 v100, v218, v219
	v_cvt_pk_bf16_f32 v101, v220, v221
	v_cvt_pk_bf16_f32 v102, v222, v223
	v_cvt_pk_bf16_f32 v103, v224, v225
	global_store_dwordx4 v228, v[100:103], s[42:43]
	s_add_u32 s42, s42, 0x8000
	s_addc_u32 s43, s43, 0
	ds_write_b128 v165, v[92:95]
	ds_write_b128 v165, v[84:87] offset:64
	ds_read_b128 v[92:95], v166
	ds_read_b128 v[84:87], v166 offset:1152
	s_waitcnt vmcnt(22)
	s_waitcnt lgkmcnt(1)
	v_lshlrev_b32_e32 v230, 16, v92
	v_and_b32_e32 v231, 0xffff0000, v92
	v_pk_add_f32 v[32:33], v[32:33], v[230:231]
	v_lshlrev_b32_e32 v230, 16, v93
	v_and_b32_e32 v231, 0xffff0000, v93
	v_pk_add_f32 v[34:35], v[34:35], v[230:231]
	v_lshlrev_b32_e32 v230, 16, v94
	v_and_b32_e32 v231, 0xffff0000, v94
	v_pk_add_f32 v[36:37], v[36:37], v[230:231]
	v_lshlrev_b32_e32 v230, 16, v95
	v_and_b32_e32 v231, 0xffff0000, v95
	v_pk_add_f32 v[38:39], v[38:39], v[230:231]
	v_cvt_pk_bf16_f32 v92, v32, v33
	v_cvt_pk_bf16_f32 v93, v34, v35
	v_cvt_pk_bf16_f32 v94, v36, v37
	v_cvt_pk_bf16_f32 v95, v38, v39
	global_store_dwordx4 v227, v[92:95], s[42:43]
	s_waitcnt lgkmcnt(0)
	v_lshlrev_b32_e32 v230, 16, v84
	v_and_b32_e32 v231, 0xffff0000, v84
	v_pk_add_f32 v[40:41], v[40:41], v[230:231]
	v_lshlrev_b32_e32 v230, 16, v85
	v_and_b32_e32 v231, 0xffff0000, v85
	v_pk_add_f32 v[42:43], v[42:43], v[230:231]
	v_lshlrev_b32_e32 v230, 16, v86
	v_and_b32_e32 v231, 0xffff0000, v86
	v_pk_add_f32 v[44:45], v[44:45], v[230:231]
	v_lshlrev_b32_e32 v230, 16, v87
	v_and_b32_e32 v231, 0xffff0000, v87
	v_pk_add_f32 v[46:47], v[46:47], v[230:231]
	v_cvt_pk_bf16_f32 v84, v40, v41
	v_cvt_pk_bf16_f32 v85, v42, v43
	v_cvt_pk_bf16_f32 v86, v44, v45
	v_cvt_pk_bf16_f32 v87, v46, v47
	global_store_dwordx4 v228, v[84:87], s[42:43]
	s_add_u32 s42, s42, 0x28000
	s_addc_u32 s43, s43, 0
	ds_write_b128 v165, v[76:79]
	ds_write_b128 v165, v[68:71] offset:64
	ds_read_b128 v[76:79], v166
	ds_read_b128 v[68:71], v166 offset:1152
	s_waitcnt vmcnt(20)
	s_waitcnt lgkmcnt(1)
	v_lshlrev_b32_e32 v230, 16, v76
	v_and_b32_e32 v231, 0xffff0000, v76
	v_pk_add_f32 v[128:129], v[128:129], v[230:231]
	v_lshlrev_b32_e32 v230, 16, v77
	v_and_b32_e32 v231, 0xffff0000, v77
	v_pk_add_f32 v[130:131], v[130:131], v[230:231]
	v_lshlrev_b32_e32 v230, 16, v78
	v_and_b32_e32 v231, 0xffff0000, v78
	v_pk_add_f32 v[136:137], v[136:137], v[230:231]
	v_lshlrev_b32_e32 v230, 16, v79
	v_and_b32_e32 v231, 0xffff0000, v79
	v_pk_add_f32 v[138:139], v[138:139], v[230:231]
	v_cvt_pk_bf16_f32 v76, v128, v129
	v_cvt_pk_bf16_f32 v77, v130, v131
	v_cvt_pk_bf16_f32 v78, v136, v137
	v_cvt_pk_bf16_f32 v79, v138, v139
	global_store_dwordx4 v227, v[76:79], s[42:43]
	s_waitcnt lgkmcnt(0)
	v_lshlrev_b32_e32 v230, 16, v68
	v_and_b32_e32 v231, 0xffff0000, v68
	v_pk_add_f32 v[112:113], v[112:113], v[230:231]
	v_lshlrev_b32_e32 v230, 16, v69
	v_and_b32_e32 v231, 0xffff0000, v69
	v_pk_add_f32 v[114:115], v[114:115], v[230:231]
	v_lshlrev_b32_e32 v230, 16, v70
	v_and_b32_e32 v231, 0xffff0000, v70
	v_pk_add_f32 v[120:121], v[120:121], v[230:231]
	v_lshlrev_b32_e32 v230, 16, v71
	v_and_b32_e32 v231, 0xffff0000, v71
	v_pk_add_f32 v[122:123], v[122:123], v[230:231]
	v_cvt_pk_bf16_f32 v68, v112, v113
	v_cvt_pk_bf16_f32 v69, v114, v115
	v_cvt_pk_bf16_f32 v70, v120, v121
	v_cvt_pk_bf16_f32 v71, v122, v123
	global_store_dwordx4 v228, v[68:71], s[42:43]
	s_add_u32 s42, s42, 0x8000
	s_addc_u32 s43, s43, 0
	ds_write_b128 v165, v[60:63]
	ds_write_b128 v165, v[52:55] offset:64
	ds_read_b128 v[60:63], v166
	ds_read_b128 v[52:55], v166 offset:1152
	s_waitcnt vmcnt(18)
	s_waitcnt lgkmcnt(1)
	v_lshlrev_b32_e32 v230, 16, v60
	v_and_b32_e32 v231, 0xffff0000, v60
	v_pk_add_f32 v[96:97], v[96:97], v[230:231]
	v_lshlrev_b32_e32 v230, 16, v61
	v_and_b32_e32 v231, 0xffff0000, v61
	v_pk_add_f32 v[98:99], v[98:99], v[230:231]
	v_lshlrev_b32_e32 v230, 16, v62
	v_and_b32_e32 v231, 0xffff0000, v62
	v_pk_add_f32 v[104:105], v[104:105], v[230:231]
	v_lshlrev_b32_e32 v230, 16, v63
	v_and_b32_e32 v231, 0xffff0000, v63
	v_pk_add_f32 v[106:107], v[106:107], v[230:231]
	v_cvt_pk_bf16_f32 v60, v96, v97
	v_cvt_pk_bf16_f32 v61, v98, v99
	v_cvt_pk_bf16_f32 v62, v104, v105
	v_cvt_pk_bf16_f32 v63, v106, v107
	global_store_dwordx4 v227, v[60:63], s[42:43]
	s_waitcnt lgkmcnt(0)
	v_lshlrev_b32_e32 v230, 16, v52
	v_and_b32_e32 v231, 0xffff0000, v52
	v_pk_add_f32 v[80:81], v[80:81], v[230:231]
	v_lshlrev_b32_e32 v230, 16, v53
	v_and_b32_e32 v231, 0xffff0000, v53
	v_pk_add_f32 v[82:83], v[82:83], v[230:231]
	v_lshlrev_b32_e32 v230, 16, v54
	v_and_b32_e32 v231, 0xffff0000, v54
	v_pk_add_f32 v[88:89], v[88:89], v[230:231]
	v_lshlrev_b32_e32 v230, 16, v55
	v_and_b32_e32 v231, 0xffff0000, v55
	v_pk_add_f32 v[90:91], v[90:91], v[230:231]
	v_cvt_pk_bf16_f32 v52, v80, v81
	v_cvt_pk_bf16_f32 v53, v82, v83
	v_cvt_pk_bf16_f32 v54, v88, v89
	v_cvt_pk_bf16_f32 v55, v90, v91
	global_store_dwordx4 v228, v[52:55], s[42:43]
	s_add_u32 s42, s42, 0x8000
	s_addc_u32 s43, s43, 0
	ds_write_b128 v165, v[28:31]
	ds_write_b128 v165, v[20:23] offset:64
	ds_read_b128 v[28:31], v166
	ds_read_b128 v[20:23], v166 offset:1152
	s_waitcnt vmcnt(16)
	s_waitcnt lgkmcnt(1)
	v_lshlrev_b32_e32 v230, 16, v28
	v_and_b32_e32 v231, 0xffff0000, v28
	v_pk_add_f32 v[64:65], v[64:65], v[230:231]
	v_lshlrev_b32_e32 v230, 16, v29
	v_and_b32_e32 v231, 0xffff0000, v29
	v_pk_add_f32 v[66:67], v[66:67], v[230:231]
	v_lshlrev_b32_e32 v230, 16, v30
	v_and_b32_e32 v231, 0xffff0000, v30
	v_pk_add_f32 v[72:73], v[72:73], v[230:231]
	v_lshlrev_b32_e32 v230, 16, v31
	v_and_b32_e32 v231, 0xffff0000, v31
	v_pk_add_f32 v[74:75], v[74:75], v[230:231]
	v_cvt_pk_bf16_f32 v28, v64, v65
	v_cvt_pk_bf16_f32 v29, v66, v67
	v_cvt_pk_bf16_f32 v30, v72, v73
	v_cvt_pk_bf16_f32 v31, v74, v75
	global_store_dwordx4 v227, v[28:31], s[42:43]
	s_waitcnt lgkmcnt(0)
	v_lshlrev_b32_e32 v230, 16, v20
	v_and_b32_e32 v231, 0xffff0000, v20
	v_pk_add_f32 v[48:49], v[48:49], v[230:231]
	v_lshlrev_b32_e32 v230, 16, v21
	v_and_b32_e32 v231, 0xffff0000, v21
	v_pk_add_f32 v[50:51], v[50:51], v[230:231]
	v_lshlrev_b32_e32 v230, 16, v22
	v_and_b32_e32 v231, 0xffff0000, v22
	v_pk_add_f32 v[56:57], v[56:57], v[230:231]
	v_lshlrev_b32_e32 v230, 16, v23
	v_and_b32_e32 v231, 0xffff0000, v23
	v_pk_add_f32 v[58:59], v[58:59], v[230:231]
	v_cvt_pk_bf16_f32 v20, v48, v49
	v_cvt_pk_bf16_f32 v21, v50, v51
	v_cvt_pk_bf16_f32 v22, v56, v57
	v_cvt_pk_bf16_f32 v23, v58, v59
	global_store_dwordx4 v228, v[20:23], s[42:43]
	s_add_u32 s42, s42, 0x8000
	s_addc_u32 s43, s43, 0
	ds_write_b128 v165, v[12:15]
	ds_write_b128 v165, v[4:7] offset:64
	ds_read_b128 v[12:15], v166
	ds_read_b128 v[4:7], v166 offset:1152
	s_waitcnt vmcnt(14)
	s_waitcnt lgkmcnt(1)
	v_lshlrev_b32_e32 v230, 16, v12
	v_and_b32_e32 v231, 0xffff0000, v12
	v_pk_add_f32 v[16:17], v[16:17], v[230:231]
	v_lshlrev_b32_e32 v230, 16, v13
	v_and_b32_e32 v231, 0xffff0000, v13
	v_pk_add_f32 v[18:19], v[18:19], v[230:231]
	v_lshlrev_b32_e32 v230, 16, v14
	v_and_b32_e32 v231, 0xffff0000, v14
	v_pk_add_f32 v[24:25], v[24:25], v[230:231]
	v_lshlrev_b32_e32 v230, 16, v15
	v_and_b32_e32 v231, 0xffff0000, v15
	v_pk_add_f32 v[26:27], v[26:27], v[230:231]
	v_cvt_pk_bf16_f32 v12, v16, v17
	v_cvt_pk_bf16_f32 v13, v18, v19
	v_cvt_pk_bf16_f32 v14, v24, v25
	v_cvt_pk_bf16_f32 v15, v26, v27
	global_store_dwordx4 v227, v[12:15], s[42:43]
	s_waitcnt lgkmcnt(0)
	v_lshlrev_b32_e32 v230, 16, v4
	v_and_b32_e32 v231, 0xffff0000, v4
	v_pk_add_f32 v[0:1], v[0:1], v[230:231]
	v_lshlrev_b32_e32 v230, 16, v5
	v_and_b32_e32 v231, 0xffff0000, v5
	v_pk_add_f32 v[2:3], v[2:3], v[230:231]
	v_lshlrev_b32_e32 v230, 16, v6
	v_and_b32_e32 v231, 0xffff0000, v6
	v_pk_add_f32 v[8:9], v[8:9], v[230:231]
	v_lshlrev_b32_e32 v230, 16, v7
	v_and_b32_e32 v231, 0xffff0000, v7
	v_pk_add_f32 v[10:11], v[10:11], v[230:231]
	v_cvt_pk_bf16_f32 v4, v0, v1
	v_cvt_pk_bf16_f32 v5, v2, v3
	v_cvt_pk_bf16_f32 v6, v8, v9
	v_cvt_pk_bf16_f32 v7, v10, v11
	global_store_dwordx4 v228, v[4:7], s[42:43]
	s_andn2_b64 vcc, exec, s[0:1]
	s_mov_b64 s[0:1], -1
	s_cbranch_vccnz .LBB0_767
	s_andn2_b64 vcc, exec, s[8:9]
	s_cbranch_vccnz .LBB0_766
	s_barrier
	s_branch .LBB0_766
